# conv phase: 7 row loads requested before the halo wait (one round trip per trip)
# baseline (speedup 1.0000x reference)
; __device__ __forceinline__ float siluf_(float x) { return x * sigmoidf_(x); }
; __device__ __forceinline__ void st_wt16(void* p, u32x4 v) { asm volatile("global_store_dwordx4 %0, %1, off sc1\n\ts_nop 1" : : "v"(p), "v"(v) : "memory"); }
; __device__ __forceinline__ void p_conv(const Params& p) {
;     ...
;         u32x4 raw[11];
; #pragma unroll
;         for (int i = 0; i < 11; ++i) {
;             const int rr = s0 - 3 + i;
;             if (seq0 + rr >= 0) raw[i] = __builtin_nontemporal_load((const u32x4*)(R1 + (size_t)(tok0 + rr) * 5120 + ch)); else raw[i] = (u32x4){0u, 0u, 0u, 0u};
;         }
; #pragma unroll
;         for (int i = 0; i < 8; ++i) {
;             float o[8];
; #pragma unroll
;             for (int e = 0; e < 8; ++e) o[e] = cb[e];
; #pragma unroll
;             for (int w = 0; w < 4; ++w) { float f[8]; unpack8(raw[i + w], f);
; #pragma unroll
;                 for (int e = 0; e < 8; ++e) o[e] += cw[w][e] * f[e]; }
; #pragma unroll
;             for (int e = 0; e < 8; ++e) o[e] = siluf_(o[e]) * scale;
;             st_wt16(QK + (size_t)(tok0 + s0 + i) * 2048 + ch, pack8(o));
;         }
.LBB0_176:
	s_or_b64 exec, exec, s[8:9]
	v_add_u32_e32 v74, s15, v102
	v_mad_i64_i32 v[42:43], s[8:9], v74, s12, v[40:41]
	global_load_dwordx4 v[86:89], v[42:43], off nt
	v_add_u32_e32 v48, s15, v108
	v_add_u32_e32 v49, s15, v109
	v_add_u32_e32 v50, s15, v110
	v_add_u32_e32 v51, s15, v111
	v_add_u32_e32 v52, s15, v112
	v_add_u32_e32 v53, s15, v113
	v_add_u32_e32 v54, s15, v105
	v_mad_i64_i32 v[130:131], s[8:9], v48, s12, v[40:41]
	global_load_dwordx4 v[144:147], v[130:131], off nt
	v_mad_i64_i32 v[132:133], s[8:9], v49, s12, v[40:41]
	global_load_dwordx4 v[148:151], v[132:133], off nt
	v_mad_i64_i32 v[134:135], s[8:9], v50, s12, v[40:41]
	global_load_dwordx4 v[152:155], v[134:135], off nt
	v_mad_i64_i32 v[136:137], s[8:9], v51, s12, v[40:41]
	global_load_dwordx4 v[156:159], v[136:137], off nt
	v_mad_i64_i32 v[138:139], s[8:9], v52, s12, v[40:41]
	global_load_dwordx4 v[160:163], v[138:139], off nt
	v_mad_i64_i32 v[140:141], s[8:9], v53, s12, v[40:41]
	global_load_dwordx4 v[164:167], v[140:141], off nt
	v_mad_i64_i32 v[142:143], s[8:9], v54, s12, v[40:41]
	global_load_dwordx4 v[168:171], v[142:143], off nt
	s_waitcnt vmcnt(0)
	v_lshlrev_b32_e32 v42, 16, v58
	v_and_b32_e32 v43, 0xffff0000, v58
	v_lshlrev_b32_e32 v90, 16, v68
	v_and_b32_e32 v91, 0xffff0000, v68
	v_lshlrev_b32_e32 v44, 16, v59
	v_and_b32_e32 v45, 0xffff0000, v59
	v_lshlrev_b32_e32 v92, 16, v69
	v_and_b32_e32 v93, 0xffff0000, v69
	v_lshlrev_b32_e32 v46, 16, v60
	v_and_b32_e32 v47, 0xffff0000, v60
	v_mad_i64_i32 v[68:69], s[8:9], v48, s12, v[40:41]
	v_lshlrev_b32_e32 v82, 16, v64
	v_and_b32_e32 v83, 0xffff0000, v64
	v_lshlrev_b32_e32 v84, 16, v65
	v_and_b32_e32 v85, 0xffff0000, v65
	v_mad_i64_i32 v[78:79], s[8:9], v49, s12, v[40:41]
	v_mad_i64_i32 v[80:81], s[8:9], v50, s12, v[40:41]
	v_mad_i64_i32 v[94:95], s[8:9], v51, s12, v[40:41]
	v_mad_i64_i32 v[96:97], s[8:9], v52, s12, v[40:41]
	v_mad_i64_i32 v[98:99], s[8:9], v53, s12, v[40:41]
	v_mad_i64_i32 v[122:123], s[8:9], v54, s12, v[40:41]
	v_pk_fma_f32 v[124:125], v[32:33], v[42:43], v[36:37]
	v_pk_fma_f32 v[126:127], v[34:35], v[44:45], v[38:39]
	s_waitcnt lgkmcnt(0)
	v_pk_fma_f32 v[128:129], v[12:13], v[46:47], v[16:17]
	v_mov_b32_e32 v116, v144
	v_mov_b32_e32 v117, v145
	v_mov_b32_e32 v118, v146
	v_mov_b32_e32 v119, v147
	v_mov_b32_e32 v62, v148
	v_mov_b32_e32 v63, v149
	v_mov_b32_e32 v64, v150
	v_mov_b32_e32 v65, v151
	v_mov_b32_e32 v56, v152
	v_mov_b32_e32 v57, v153
	v_mov_b32_e32 v58, v154
	v_mov_b32_e32 v59, v155
	v_mov_b32_e32 v52, v156
	v_mov_b32_e32 v53, v157
	v_mov_b32_e32 v54, v158
	v_mov_b32_e32 v55, v159
	v_mov_b32_e32 v48, v160
	v_mov_b32_e32 v49, v161
	v_mov_b32_e32 v50, v162
	v_mov_b32_e32 v51, v163
	v_mov_b32_e32 v44, v164
	v_mov_b32_e32 v45, v165
	v_mov_b32_e32 v46, v166
	v_mov_b32_e32 v47, v167
	v_mov_b32_e32 v40, v168
	v_mov_b32_e32 v41, v169
	v_mov_b32_e32 v42, v170
	v_mov_b32_e32 v43, v171
	v_lshlrev_b32_e32 v120, 16, v70
	v_and_b32_e32 v121, 0xffff0000, v70
	v_lshlrev_b32_e32 v100, 16, v66
	v_and_b32_e32 v101, 0xffff0000, v66
	v_pk_fma_f32 v[68:69], v[28:29], v[90:91], v[124:125]
	v_pk_fma_f32 v[80:81], v[0:1], v[120:121], v[128:129]
	v_pk_fma_f32 v[78:79], v[30:31], v[92:93], v[126:127]
	v_pk_fma_f32 v[94:95], v[24:25], v[82:83], v[68:69]
	v_pk_fma_f32 v[98:99], v[4:5], v[100:101], v[80:81]
	v_pk_fma_f32 v[96:97], v[26:27], v[84:85], v[78:79]
	v_lshl_add_u64 v[76:77], s[94:95], 0, v[72:73]
	s_cmp_gt_u32 s14, 3
	s_cselect_b64 vcc, -1, 0
	v_cndmask_b32_e32 v60, 1.0, v114, vcc
	v_ashrrev_i32_e32 v75, 31, v74
	s_add_i32 s13, s13, s82
	s_add_i32 s10, s10, s11
	s_cmpk_lt_i32 s13, 0x400
	v_lshlrev_b32_e32 v80, 16, v86
	v_and_b32_e32 v81, 0xffff0000, v86
	v_lshlrev_b32_e32 v78, 16, v87
	v_and_b32_e32 v79, 0xffff0000, v87
	v_pk_fma_f32 v[86:87], v[20:21], v[80:81], v[94:95]
	v_pk_fma_f32 v[94:95], v[22:23], v[78:79], v[96:97]
	v_mul_f32_e32 v66, 0xbfb8aa3b, v86
	v_mul_f32_e32 v70, 0xbfb8aa3b, v87
	v_exp_f32_e32 v66, v66
	v_exp_f32_e32 v70, v70
	v_lshlrev_b32_e32 v68, 16, v88
	v_and_b32_e32 v69, 0xffff0000, v88
	v_mul_f32_e32 v72, 0xbfb8aa3b, v94
	v_mul_f32_e32 v88, 0xbfb8aa3b, v95
	v_exp_f32_e32 v72, v72
	v_exp_f32_e32 v88, v88
	v_pk_fma_f32 v[96:97], v[8:9], v[68:69], v[98:99]
	v_add_f32_e32 v66, 1.0, v66
	v_add_f32_e32 v70, 1.0, v70
	v_mul_f32_e32 v124, 0xbfb8aa3b, v97
	v_rcp_f32_e32 v98, v66
	v_rcp_f32_e32 v99, v70
	v_add_f32_e32 v72, 1.0, v72
	v_add_f32_e32 v88, 1.0, v88
	v_exp_f32_e32 v70, v124
	v_rcp_f32_e32 v122, v72
	v_rcp_f32_e32 v123, v88
	v_pk_mul_f32 v[86:87], v[86:87], v[98:99]
	v_lshlrev_b32_e32 v98, 16, v61
	v_and_b32_e32 v99, 0xffff0000, v61
	v_add_f32_e32 v72, 1.0, v70
	v_pk_fma_f32 v[98:99], v[14:15], v[98:99], v[18:19]
	v_lshlrev_b32_e32 v70, 16, v71
	v_and_b32_e32 v71, 0xffff0000, v71
	v_pk_mul_f32 v[94:95], v[94:95], v[122:123]
	v_pk_fma_f32 v[98:99], v[2:3], v[70:71], v[98:99]
	v_lshlrev_b32_e32 v122, 16, v67
	v_and_b32_e32 v123, 0xffff0000, v67
	v_pk_fma_f32 v[124:125], v[6:7], v[122:123], v[98:99]
	v_lshlrev_b32_e32 v98, 16, v89
	v_and_b32_e32 v99, 0xffff0000, v89
	v_pk_fma_f32 v[88:89], v[10:11], v[98:99], v[124:125]
	v_pk_mul_f32 v[86:87], v[60:61], v[86:87] op_sel_hi:[0,1]
	v_mul_f32_e32 v61, 0xbfb8aa3b, v88
	v_mul_f32_e32 v115, 0xbfb8aa3b, v96
	v_exp_f32_e32 v61, v61
	v_mul_f32_e32 v67, 0xbfb8aa3b, v89
	v_exp_f32_e32 v66, v115
	v_exp_f32_e32 v115, v67
	v_add_f32_e32 v61, 1.0, v61
	v_rcp_f32_e32 v124, v61
	v_add_f32_e32 v66, 1.0, v66
	v_add_f32_e32 v61, 1.0, v115
	v_rcp_f32_e32 v125, v61
	v_rcp_f32_e32 v66, v66
	v_rcp_f32_e32 v67, v72
	v_pk_mul_f32 v[94:95], v[60:61], v[94:95] op_sel_hi:[0,1]
	v_pk_mul_f32 v[88:89], v[88:89], v[124:125]
	v_cvt_pk_bf16_f32 v86, v86, v87
	v_pk_mul_f32 v[124:125], v[60:61], v[88:89] op_sel_hi:[0,1]
	v_lshlrev_b64 v[88:89], 12, v[74:75]
	v_lshl_add_u64 v[126:127], v[76:77], 0, v[88:89]
	v_pk_fma_f32 v[88:89], v[32:33], v[90:91], v[36:37]
	v_pk_mul_f32 v[66:67], v[96:97], v[66:67]
	v_pk_fma_f32 v[88:89], v[28:29], v[82:83], v[88:89]
	s_waitcnt vmcnt(6)
; __device__ __forceinline__ float siluf_(float x) { return x * sigmoidf_(x); }
; __device__ __forceinline__ void st_wt16(void* p, u32x4 v) { asm volatile("global_store_dwordx4 %0, %1, off sc1\n\ts_nop 1" : : "v"(p), "v"(v) : "memory"); }
; __device__ __forceinline__ void p_conv(const Params& p) {
;     ...
;         u32x4 raw[11];
; #pragma unroll
;         for (int i = 0; i < 11; ++i) {
;             const int rr = s0 - 3 + i;
;             if (seq0 + rr >= 0) raw[i] = __builtin_nontemporal_load((const u32x4*)(R1 + (size_t)(tok0 + rr) * 5120 + ch)); else raw[i] = (u32x4){0u, 0u, 0u, 0u};
;         }
; #pragma unroll
;         for (int i = 0; i < 8; ++i) {
;             float o[8];
; #pragma unroll
;             for (int e = 0; e < 8; ++e) o[e] = cb[e];
; #pragma unroll
;             for (int w = 0; w < 4; ++w) { float f[8]; unpack8(raw[i + w], f);
; #pragma unroll
;                 for (int e = 0; e < 8; ++e) o[e] += cw[w][e] * f[e]; }
; #pragma unroll
;             for (int e = 0; e < 8; ++e) o[e] = siluf_(o[e]) * scale;
;             st_wt16(QK + (size_t)(tok0 + s0 + i) * 2048 + ch, pack8(o));
;         }
	v_lshlrev_b32_e32 v96, 16, v116
	v_pk_fma_f32 v[88:89], v[24:25], v[80:81], v[88:89]
	v_and_b32_e32 v97, 0xffff0000, v116
	v_pk_fma_f32 v[90:91], v[20:21], v[96:97], v[88:89]
	v_pk_mul_f32 v[66:67], v[60:61], v[66:67] op_sel_hi:[0,1]
	v_mul_f32_e32 v61, 0xbfb8aa3b, v90
	v_exp_f32_e32 v61, v61
	v_mul_f32_e32 v72, 0xbfb8aa3b, v91
	v_exp_f32_e32 v72, v72
	v_cvt_pk_bf16_f32 v87, v94, v95
	v_add_f32_e32 v61, 1.0, v61
	v_rcp_f32_e32 v94, v61
	v_add_f32_e32 v61, 1.0, v72
	v_rcp_f32_e32 v95, v61
	v_cvt_pk_bf16_f32 v88, v66, v67
	v_cvt_pk_bf16_f32 v89, v124, v125
	global_store_dwordx4 v[126:127], v[86:89], off sc1
	s_nop 1
	v_pk_fma_f32 v[86:87], v[34:35], v[92:93], v[38:39]
	v_pk_mul_f32 v[66:67], v[90:91], v[94:95]
	v_pk_fma_f32 v[86:87], v[30:31], v[84:85], v[86:87]
	v_lshlrev_b32_e32 v94, 16, v117
	v_pk_fma_f32 v[86:87], v[26:27], v[78:79], v[86:87]
	v_and_b32_e32 v95, 0xffff0000, v117
	v_pk_fma_f32 v[86:87], v[22:23], v[94:95], v[86:87]
	v_pk_fma_f32 v[90:91], v[12:13], v[120:121], v[16:17]
	v_mul_f32_e32 v61, 0xbfb8aa3b, v86
	v_exp_f32_e32 v61, v61
	v_mul_f32_e32 v72, 0xbfb8aa3b, v87
	v_exp_f32_e32 v72, v72
	v_pk_fma_f32 v[90:91], v[0:1], v[100:101], v[90:91]
	v_pk_mul_f32 v[66:67], v[60:61], v[66:67] op_sel_hi:[0,1]
	v_add_f32_e32 v61, 1.0, v61
	v_pk_fma_f32 v[90:91], v[4:5], v[68:69], v[90:91]
	v_lshlrev_b32_e32 v92, 16, v118
	v_and_b32_e32 v93, 0xffff0000, v118
	v_rcp_f32_e32 v88, v61
	v_add_f32_e32 v61, 1.0, v72
	v_pk_fma_f32 v[116:117], v[8:9], v[92:93], v[90:91]
	v_rcp_f32_e32 v89, v61
	v_mul_f32_e32 v61, 0xbfb8aa3b, v116
	v_exp_f32_e32 v61, v61
	v_mul_f32_e32 v72, 0xbfb8aa3b, v117
	v_exp_f32_e32 v72, v72
	v_pk_fma_f32 v[70:71], v[14:15], v[70:71], v[18:19]
	v_lshlrev_b32_e32 v90, 16, v119
	v_pk_fma_f32 v[70:71], v[2:3], v[122:123], v[70:71]
	v_and_b32_e32 v91, 0xffff0000, v119
	v_pk_fma_f32 v[70:71], v[6:7], v[98:99], v[70:71]
	v_add_f32_e32 v61, 1.0, v61
	v_pk_fma_f32 v[70:71], v[10:11], v[90:91], v[70:71]
	v_pk_mul_f32 v[86:87], v[86:87], v[88:89]
	v_rcp_f32_e32 v88, v61
	v_add_f32_e32 v61, 1.0, v72
	v_mul_f32_e32 v72, 0xbfb8aa3b, v70
	v_exp_f32_e32 v72, v72
	v_mul_f32_e32 v75, 0xbfb8aa3b, v71
	v_exp_f32_e32 v75, v75
	v_rcp_f32_e32 v89, v61
	v_add_f32_e32 v61, 1.0, v72
	v_rcp_f32_e32 v118, v61
	v_add_f32_e32 v61, 1.0, v75
	v_pk_mul_f32 v[88:89], v[116:117], v[88:89]
	v_rcp_f32_e32 v119, v61
	v_pk_mul_f32 v[120:121], v[60:61], v[88:89] op_sel_hi:[0,1]
	v_or_b32_e32 v88, 1, v74
	v_ashrrev_i32_e32 v89, 31, v88
	v_cvt_pk_bf16_f32 v116, v66, v67
	v_pk_fma_f32 v[66:67], v[32:33], v[82:83], v[36:37]
	v_lshlrev_b64 v[88:89], 12, v[88:89]
	v_pk_fma_f32 v[66:67], v[28:29], v[80:81], v[66:67]
	v_lshl_add_u64 v[124:125], v[76:77], 0, v[88:89]
	v_pk_fma_f32 v[66:67], v[24:25], v[96:97], v[66:67]
	s_waitcnt vmcnt(5)
	v_lshlrev_b32_e32 v88, 16, v62
	v_and_b32_e32 v89, 0xffff0000, v62
	v_pk_mul_f32 v[70:71], v[70:71], v[118:119]
	v_pk_fma_f32 v[66:67], v[20:21], v[88:89], v[66:67]
	v_pk_mul_f32 v[86:87], v[60:61], v[86:87] op_sel_hi:[0,1]
	v_pk_mul_f32 v[70:71], v[60:61], v[70:71] op_sel_hi:[0,1]
	v_mul_f32_e32 v61, 0xbfb8aa3b, v66
	v_exp_f32_e32 v61, v61
	v_mul_f32_e32 v62, 0xbfb8aa3b, v67
	v_exp_f32_e32 v62, v62
	v_cvt_pk_bf16_f32 v119, v70, v71
	v_pk_fma_f32 v[70:71], v[34:35], v[84:85], v[38:39]
	v_cvt_pk_bf16_f32 v117, v86, v87
	v_pk_fma_f32 v[70:71], v[30:31], v[78:79], v[70:71]
	v_add_f32_e32 v61, 1.0, v61
	v_pk_fma_f32 v[70:71], v[26:27], v[94:95], v[70:71]
	v_lshlrev_b32_e32 v86, 16, v63
	v_and_b32_e32 v87, 0xffff0000, v63
	v_rcp_f32_e32 v82, v61
	v_add_f32_e32 v61, 1.0, v62
	v_pk_fma_f32 v[62:63], v[22:23], v[86:87], v[70:71]
	v_rcp_f32_e32 v83, v61
	v_mul_f32_e32 v61, 0xbfb8aa3b, v62
	v_exp_f32_e32 v61, v61
	v_mul_f32_e32 v70, 0xbfb8aa3b, v63
	v_exp_f32_e32 v71, v70
	v_pk_mul_f32 v[66:67], v[66:67], v[82:83]
	v_pk_fma_f32 v[82:83], v[12:13], v[100:101], v[16:17]
	v_pk_mul_f32 v[66:67], v[60:61], v[66:67] op_sel_hi:[0,1]
	v_add_f32_e32 v61, 1.0, v61
	v_rcp_f32_e32 v70, v61
	v_add_f32_e32 v61, 1.0, v71
	v_rcp_f32_e32 v71, v61
	v_pk_fma_f32 v[82:83], v[0:1], v[68:69], v[82:83]
	v_lshlrev_b32_e32 v84, 16, v64
	v_pk_fma_f32 v[82:83], v[4:5], v[92:93], v[82:83]
	v_and_b32_e32 v85, 0xffff0000, v64
	v_pk_fma_f32 v[100:101], v[8:9], v[84:85], v[82:83]
	v_pk_mul_f32 v[62:63], v[62:63], v[70:71]
	v_mul_f32_e32 v61, 0xbfb8aa3b, v100
	v_exp_f32_e32 v61, v61
	v_mul_f32_e32 v64, 0xbfb8aa3b, v101
	v_pk_fma_f32 v[70:71], v[14:15], v[122:123], v[18:19]
	v_exp_f32_e32 v72, v64
	v_pk_fma_f32 v[70:71], v[2:3], v[98:99], v[70:71]
	v_lshlrev_b32_e32 v82, 16, v65
	v_pk_fma_f32 v[70:71], v[6:7], v[90:91], v[70:71]
	v_and_b32_e32 v83, 0xffff0000, v65
	v_pk_fma_f32 v[70:71], v[10:11], v[82:83], v[70:71]
	v_add_f32_e32 v61, 1.0, v61
	v_mul_f32_e32 v65, 0xbfb8aa3b, v70
	v_rcp_f32_e32 v64, v61
	v_add_f32_e32 v61, 1.0, v72
	v_exp_f32_e32 v72, v65
	v_mul_f32_e32 v65, 0xbfb8aa3b, v71
	v_exp_f32_e32 v75, v65
	v_rcp_f32_e32 v65, v61
	v_add_f32_e32 v61, 1.0, v72
	v_cvt_pk_bf16_f32 v118, v120, v121
	global_store_dwordx4 v[124:125], v[116:119], off sc1
	s_nop 1
	v_rcp_f32_e32 v116, v61
	v_add_f32_e32 v61, 1.0, v75
	v_rcp_f32_e32 v117, v61
	v_pk_mul_f32 v[118:119], v[60:61], v[62:63] op_sel_hi:[0,1]
	v_pk_mul_f32 v[62:63], v[100:101], v[64:65]
	s_nop 0
	v_pk_mul_f32 v[64:65], v[60:61], v[62:63] op_sel_hi:[0,1]
	v_pk_mul_f32 v[62:63], v[70:71], v[116:117]
	v_cvt_pk_bf16_f32 v64, v64, v65
	v_pk_mul_f32 v[70:71], v[60:61], v[62:63] op_sel_hi:[0,1]
	v_or_b32_e32 v62, 2, v74
	v_ashrrev_i32_e32 v63, 31, v62
	v_lshlrev_b64 v[62:63], 12, v[62:63]
	v_lshl_add_u64 v[100:101], v[76:77], 0, v[62:63]
	v_cvt_pk_bf16_f32 v62, v66, v67
	v_pk_fma_f32 v[66:67], v[32:33], v[80:81], v[36:37]
	s_waitcnt vmcnt(4)
; __device__ __forceinline__ float siluf_(float x) { return x * sigmoidf_(x); }
; __device__ __forceinline__ void st_wt16(void* p, u32x4 v) { asm volatile("global_store_dwordx4 %0, %1, off sc1\n\ts_nop 1" : : "v"(p), "v"(v) : "memory"); }
; __device__ __forceinline__ void p_conv(const Params& p) {
;     ...
;         u32x4 raw[11];
; #pragma unroll
;         for (int i = 0; i < 11; ++i) {
;             const int rr = s0 - 3 + i;
;             if (seq0 + rr >= 0) raw[i] = __builtin_nontemporal_load((const u32x4*)(R1 + (size_t)(tok0 + rr) * 5120 + ch)); else raw[i] = (u32x4){0u, 0u, 0u, 0u};
;         }
; #pragma unroll
;         for (int i = 0; i < 8; ++i) {
;             float o[8];
; #pragma unroll
;             for (int e = 0; e < 8; ++e) o[e] = cb[e];
; #pragma unroll
;             for (int w = 0; w < 4; ++w) { float f[8]; unpack8(raw[i + w], f);
; #pragma unroll
;                 for (int e = 0; e < 8; ++e) o[e] += cw[w][e] * f[e]; }
; #pragma unroll
;             for (int e = 0; e < 8; ++e) o[e] = siluf_(o[e]) * scale;
;             st_wt16(QK + (size_t)(tok0 + s0 + i) * 2048 + ch, pack8(o));
;         }
	v_lshlrev_b32_e32 v80, 16, v56
	v_pk_fma_f32 v[66:67], v[28:29], v[96:97], v[66:67]
	v_and_b32_e32 v81, 0xffff0000, v56
	v_pk_fma_f32 v[66:67], v[24:25], v[88:89], v[66:67]
	v_cvt_pk_bf16_f32 v65, v70, v71
	v_pk_fma_f32 v[66:67], v[20:21], v[80:81], v[66:67]
	v_cvt_pk_bf16_f32 v63, v118, v119
	v_mul_f32_e32 v56, 0xbfb8aa3b, v66
	v_exp_f32_e32 v56, v56
	v_mul_f32_e32 v61, 0xbfb8aa3b, v67
	v_exp_f32_e32 v61, v61
	global_store_dwordx4 v[100:101], v[62:65], off sc1
	s_nop 1
	v_pk_fma_f32 v[64:65], v[34:35], v[78:79], v[38:39]
	v_add_f32_e32 v56, 1.0, v56
	v_pk_fma_f32 v[64:65], v[30:31], v[94:95], v[64:65]
	v_rcp_f32_e32 v116, v56
	v_add_f32_e32 v56, 1.0, v61
	v_pk_fma_f32 v[64:65], v[26:27], v[86:87], v[64:65]
	v_lshlrev_b32_e32 v70, 16, v57
	v_and_b32_e32 v71, 0xffff0000, v57
	v_rcp_f32_e32 v117, v56
	v_pk_fma_f32 v[56:57], v[22:23], v[70:71], v[64:65]
	v_pk_mul_f32 v[62:63], v[66:67], v[116:117]
	v_mul_f32_e32 v61, 0xbfb8aa3b, v56
	v_exp_f32_e32 v61, v61
	v_mul_f32_e32 v64, 0xbfb8aa3b, v57
	v_exp_f32_e32 v65, v64
	v_pk_fma_f32 v[66:67], v[12:13], v[68:69], v[16:17]
	v_pk_mul_f32 v[62:63], v[60:61], v[62:63] op_sel_hi:[0,1]
	v_add_f32_e32 v61, 1.0, v61
	v_rcp_f32_e32 v64, v61
	v_add_f32_e32 v61, 1.0, v65
	v_rcp_f32_e32 v65, v61
	v_pk_fma_f32 v[66:67], v[0:1], v[92:93], v[66:67]
	v_pk_mul_f32 v[56:57], v[56:57], v[64:65]
	v_pk_fma_f32 v[64:65], v[14:15], v[98:99], v[18:19]
	v_pk_fma_f32 v[68:69], v[4:5], v[84:85], v[66:67]
	v_lshlrev_b32_e32 v66, 16, v58
	v_and_b32_e32 v67, 0xffff0000, v58
	v_pk_fma_f32 v[64:65], v[2:3], v[90:91], v[64:65]
	v_pk_fma_f32 v[68:69], v[8:9], v[66:67], v[68:69]
	v_pk_fma_f32 v[78:79], v[6:7], v[82:83], v[64:65]
	v_lshlrev_b32_e32 v64, 16, v59
	v_and_b32_e32 v65, 0xffff0000, v59
	v_mul_f32_e32 v61, 0xbfb8aa3b, v69
	v_pk_fma_f32 v[78:79], v[10:11], v[64:65], v[78:79]
	v_mul_f32_e32 v58, 0xbfb8aa3b, v68
	v_exp_f32_e32 v61, v61
	v_mul_f32_e32 v59, 0xbfb8aa3b, v78
	v_exp_f32_e32 v58, v58
	v_exp_f32_e32 v72, v59
	v_mul_f32_e32 v59, 0xbfb8aa3b, v79
	v_exp_f32_e32 v75, v59
	v_add_f32_e32 v61, 1.0, v61
	v_add_f32_e32 v58, 1.0, v58
	v_rcp_f32_e32 v59, v61
	v_add_f32_e32 v61, 1.0, v72
	v_rcp_f32_e32 v58, v58
	v_rcp_f32_e32 v98, v61
	v_add_f32_e32 v61, 1.0, v75
	v_rcp_f32_e32 v99, v61
	v_pk_mul_f32 v[100:101], v[60:61], v[56:57] op_sel_hi:[0,1]
	v_pk_mul_f32 v[56:57], v[68:69], v[58:59]
	s_nop 0
	v_pk_mul_f32 v[58:59], v[60:61], v[56:57] op_sel_hi:[0,1]
	v_pk_mul_f32 v[56:57], v[78:79], v[98:99]
	v_cvt_pk_bf16_f32 v58, v58, v59
	v_pk_mul_f32 v[68:69], v[60:61], v[56:57] op_sel_hi:[0,1]
	v_or_b32_e32 v56, 3, v74
	v_ashrrev_i32_e32 v57, 31, v56
	v_lshlrev_b64 v[56:57], 12, v[56:57]
	v_lshl_add_u64 v[78:79], v[76:77], 0, v[56:57]
	v_cvt_pk_bf16_f32 v56, v62, v63
	v_pk_fma_f32 v[62:63], v[32:33], v[96:97], v[36:37]
	v_cvt_pk_bf16_f32 v59, v68, v69
	v_pk_fma_f32 v[62:63], v[28:29], v[88:89], v[62:63]
	s_nop 0
	v_pk_fma_f32 v[96:97], v[24:25], v[80:81], v[62:63]
	s_waitcnt vmcnt(3)
	v_lshlrev_b32_e32 v62, 16, v52
	v_and_b32_e32 v63, 0xffff0000, v52
	v_pk_fma_f32 v[96:97], v[20:21], v[62:63], v[96:97]
	s_nop 0
	v_mul_f32_e32 v52, 0xbfb8aa3b, v96
	v_exp_f32_e32 v52, v52
	v_mul_f32_e32 v57, 0xbfb8aa3b, v97
	v_exp_f32_e32 v61, v57
	v_cvt_pk_bf16_f32 v57, v100, v101
	global_store_dwordx4 v[78:79], v[56:59], off sc1
	s_nop 1
	v_pk_fma_f32 v[58:59], v[34:35], v[94:95], v[38:39]
	v_add_f32_e32 v52, 1.0, v52
	v_pk_fma_f32 v[58:59], v[30:31], v[86:87], v[58:59]
	v_rcp_f32_e32 v98, v52
	v_add_f32_e32 v52, 1.0, v61
	v_pk_fma_f32 v[68:69], v[26:27], v[70:71], v[58:59]
	v_lshlrev_b32_e32 v58, 16, v53
	v_and_b32_e32 v59, 0xffff0000, v53
	v_rcp_f32_e32 v99, v52
	v_pk_fma_f32 v[52:53], v[22:23], v[58:59], v[68:69]
	v_pk_mul_f32 v[56:57], v[96:97], v[98:99]
	v_mul_f32_e32 v61, 0xbfb8aa3b, v52
	v_exp_f32_e32 v61, v61
	v_mul_f32_e32 v68, 0xbfb8aa3b, v53
	v_exp_f32_e32 v72, v68
	v_pk_mul_f32 v[68:69], v[60:61], v[56:57] op_sel_hi:[0,1]
	v_add_f32_e32 v56, 1.0, v61
	v_rcp_f32_e32 v78, v56
	v_add_f32_e32 v56, 1.0, v72
	v_rcp_f32_e32 v79, v56
	v_pk_fma_f32 v[56:57], v[12:13], v[92:93], v[16:17]
	v_pk_mul_f32 v[78:79], v[52:53], v[78:79]
	v_pk_fma_f32 v[56:57], v[0:1], v[84:85], v[56:57]
	v_pk_fma_f32 v[84:85], v[12:13], v[84:85], v[16:17]
	v_pk_fma_f32 v[92:93], v[4:5], v[66:67], v[56:57]
	v_lshlrev_b32_e32 v56, 16, v54
	v_and_b32_e32 v57, 0xffff0000, v54
	v_pk_fma_f32 v[92:93], v[8:9], v[56:57], v[92:93]
	v_pk_fma_f32 v[84:85], v[0:1], v[66:67], v[84:85]
	v_mul_f32_e32 v54, 0xbfb8aa3b, v92
	v_exp_f32_e32 v54, v54
	v_mul_f32_e32 v61, 0xbfb8aa3b, v93
	v_exp_f32_e32 v61, v61
	v_pk_fma_f32 v[84:85], v[4:5], v[56:57], v[84:85]
	v_add_f32_e32 v52, 1.0, v54
	v_rcp_f32_e32 v54, v52
	v_pk_fma_f32 v[52:53], v[14:15], v[90:91], v[18:19]
	v_add_f32_e32 v61, 1.0, v61
	v_pk_fma_f32 v[52:53], v[2:3], v[82:83], v[52:53]
	v_pk_fma_f32 v[66:67], v[12:13], v[66:67], v[16:17]
	v_pk_fma_f32 v[90:91], v[6:7], v[64:65], v[52:53]
	v_lshlrev_b32_e32 v52, 16, v55
	v_and_b32_e32 v53, 0xffff0000, v55
	v_pk_fma_f32 v[90:91], v[10:11], v[52:53], v[90:91]
	v_pk_fma_f32 v[66:67], v[0:1], v[56:57], v[66:67]
	v_mul_f32_e32 v55, 0xbfb8aa3b, v90
	v_exp_f32_e32 v72, v55
	v_mul_f32_e32 v55, 0xbfb8aa3b, v91
	v_exp_f32_e32 v75, v55
	v_rcp_f32_e32 v55, v61
	v_add_f32_e32 v61, 1.0, v72
	v_rcp_f32_e32 v94, v61
	v_add_f32_e32 v61, 1.0, v75
	v_rcp_f32_e32 v95, v61
	v_pk_mul_f32 v[54:55], v[92:93], v[54:55]
	v_pk_mul_f32 v[78:79], v[60:61], v[78:79] op_sel_hi:[0,1]
	v_pk_mul_f32 v[54:55], v[60:61], v[54:55] op_sel_hi:[0,1]
	v_pk_mul_f32 v[90:91], v[90:91], v[94:95]
	v_cvt_pk_bf16_f32 v92, v54, v55
	v_pk_mul_f32 v[94:95], v[60:61], v[90:91] op_sel_hi:[0,1]
	v_or_b32_e32 v90, 4, v74
	v_ashrrev_i32_e32 v91, 31, v90
	v_lshlrev_b64 v[90:91], 12, v[90:91]
	v_lshl_add_u64 v[96:97], v[76:77], 0, v[90:91]
	v_cvt_pk_bf16_f32 v90, v68, v69
	v_pk_fma_f32 v[68:69], v[32:33], v[88:89], v[36:37]
	s_waitcnt vmcnt(2)
; __device__ __forceinline__ float siluf_(float x) { return x * sigmoidf_(x); }
; __device__ __forceinline__ void st_wt16(void* p, u32x4 v) { asm volatile("global_store_dwordx4 %0, %1, off sc1\n\ts_nop 1" : : "v"(p), "v"(v) : "memory"); }
; __device__ __forceinline__ void p_conv(const Params& p) {
;     ...
;         u32x4 raw[11];
; #pragma unroll
;         for (int i = 0; i < 11; ++i) {
;             const int rr = s0 - 3 + i;
;             if (seq0 + rr >= 0) raw[i] = __builtin_nontemporal_load((const u32x4*)(R1 + (size_t)(tok0 + rr) * 5120 + ch)); else raw[i] = (u32x4){0u, 0u, 0u, 0u};
;         }
; #pragma unroll
;         for (int i = 0; i < 8; ++i) {
;             float o[8];
; #pragma unroll
;             for (int e = 0; e < 8; ++e) o[e] = cb[e];
; #pragma unroll
;             for (int w = 0; w < 4; ++w) { float f[8]; unpack8(raw[i + w], f);
; #pragma unroll
;                 for (int e = 0; e < 8; ++e) o[e] += cw[w][e] * f[e]; }
; #pragma unroll
;             for (int e = 0; e < 8; ++e) o[e] = siluf_(o[e]) * scale;
;             st_wt16(QK + (size_t)(tok0 + s0 + i) * 2048 + ch, pack8(o));
;         }
	v_lshlrev_b32_e32 v88, 16, v48
	v_pk_fma_f32 v[68:69], v[28:29], v[80:81], v[68:69]
	v_and_b32_e32 v89, 0xffff0000, v48
	v_pk_fma_f32 v[68:69], v[24:25], v[62:63], v[68:69]
	v_cvt_pk_bf16_f32 v91, v78, v79
	v_pk_fma_f32 v[68:69], v[20:21], v[88:89], v[68:69]
	v_cvt_pk_bf16_f32 v93, v94, v95
	v_mul_f32_e32 v48, 0xbfb8aa3b, v68
	v_exp_f32_e32 v48, v48
	v_mul_f32_e32 v61, 0xbfb8aa3b, v69
	v_exp_f32_e32 v61, v61
	global_store_dwordx4 v[96:97], v[90:93], off sc1
	s_nop 1
	v_add_f32_e32 v48, 1.0, v48
	v_rcp_f32_e32 v78, v48
	v_add_f32_e32 v48, 1.0, v61
	v_rcp_f32_e32 v79, v48
	v_pk_fma_f32 v[12:13], v[12:13], v[56:57], v[16:17]
	v_pk_mul_f32 v[54:55], v[68:69], v[78:79]
	v_pk_fma_f32 v[68:69], v[34:35], v[86:87], v[38:39]
	v_lshlrev_b32_e32 v78, 16, v49
	v_pk_fma_f32 v[68:69], v[30:31], v[70:71], v[68:69]
	v_and_b32_e32 v79, 0xffff0000, v49
	v_pk_fma_f32 v[68:69], v[26:27], v[58:59], v[68:69]
	v_lshlrev_b32_e32 v86, 16, v50
	v_pk_fma_f32 v[48:49], v[22:23], v[78:79], v[68:69]
	v_and_b32_e32 v87, 0xffff0000, v50
	v_mul_f32_e32 v61, 0xbfb8aa3b, v48
	v_exp_f32_e32 v61, v61
	v_mul_f32_e32 v68, 0xbfb8aa3b, v49
	v_exp_f32_e32 v69, v68
	v_pk_fma_f32 v[84:85], v[8:9], v[86:87], v[84:85]
	v_pk_mul_f32 v[54:55], v[60:61], v[54:55] op_sel_hi:[0,1]
	v_add_f32_e32 v61, 1.0, v61
	v_rcp_f32_e32 v68, v61
	v_add_f32_e32 v61, 1.0, v69
	v_rcp_f32_e32 v69, v61
	v_mul_f32_e32 v61, 0xbfb8aa3b, v85
	v_mul_f32_e32 v50, 0xbfb8aa3b, v84
	v_exp_f32_e32 v61, v61
	v_pk_mul_f32 v[48:49], v[48:49], v[68:69]
	v_pk_fma_f32 v[68:69], v[14:15], v[82:83], v[18:19]
	v_lshlrev_b32_e32 v82, 16, v51
	v_pk_fma_f32 v[68:69], v[2:3], v[64:65], v[68:69]
	v_and_b32_e32 v83, 0xffff0000, v51
	v_pk_fma_f32 v[68:69], v[6:7], v[52:53], v[68:69]
	v_exp_f32_e32 v50, v50
	v_pk_fma_f32 v[68:69], v[10:11], v[82:83], v[68:69]
	v_add_f32_e32 v61, 1.0, v61
	v_mul_f32_e32 v51, 0xbfb8aa3b, v68
	v_exp_f32_e32 v72, v51
	v_mul_f32_e32 v51, 0xbfb8aa3b, v69
	v_exp_f32_e32 v75, v51
	v_add_f32_e32 v50, 1.0, v50
	v_rcp_f32_e32 v51, v61
	v_add_f32_e32 v61, 1.0, v72
	v_rcp_f32_e32 v50, v50
	v_rcp_f32_e32 v90, v61
	v_add_f32_e32 v61, 1.0, v75
	v_rcp_f32_e32 v91, v61
	v_pk_mul_f32 v[92:93], v[60:61], v[48:49] op_sel_hi:[0,1]
	v_pk_mul_f32 v[48:49], v[84:85], v[50:51]
	v_pk_fma_f32 v[66:67], v[4:5], v[86:87], v[66:67]
	v_pk_mul_f32 v[50:51], v[60:61], v[48:49] op_sel_hi:[0,1]
	v_pk_mul_f32 v[48:49], v[68:69], v[90:91]
	v_cvt_pk_bf16_f32 v50, v50, v51
	v_pk_mul_f32 v[68:69], v[60:61], v[48:49] op_sel_hi:[0,1]
	v_or_b32_e32 v48, 5, v74
	v_ashrrev_i32_e32 v49, 31, v48
	v_lshlrev_b64 v[48:49], 12, v[48:49]
	v_lshl_add_u64 v[84:85], v[76:77], 0, v[48:49]
	v_cvt_pk_bf16_f32 v48, v54, v55
	v_pk_fma_f32 v[54:55], v[32:33], v[80:81], v[36:37]
	s_waitcnt vmcnt(1)
	v_lshlrev_b32_e32 v80, 16, v44
	v_pk_fma_f32 v[54:55], v[28:29], v[62:63], v[54:55]
	v_and_b32_e32 v81, 0xffff0000, v44
	v_pk_fma_f32 v[54:55], v[24:25], v[88:89], v[54:55]
	v_cvt_pk_bf16_f32 v51, v68, v69
	v_pk_fma_f32 v[54:55], v[20:21], v[80:81], v[54:55]
	v_pk_fma_f32 v[32:33], v[32:33], v[62:63], v[36:37]
	v_mul_f32_e32 v44, 0xbfb8aa3b, v54
	v_exp_f32_e32 v44, v44
	v_mul_f32_e32 v49, 0xbfb8aa3b, v55
	v_exp_f32_e32 v61, v49
	v_cvt_pk_bf16_f32 v49, v92, v93
	v_add_f32_e32 v44, 1.0, v44
	v_rcp_f32_e32 v90, v44
	v_add_f32_e32 v44, 1.0, v61
	v_rcp_f32_e32 v91, v44
	global_store_dwordx4 v[84:85], v[48:51], off sc1
	s_nop 1
	v_pk_fma_f32 v[50:51], v[34:35], v[70:71], v[38:39]
	v_pk_fma_f32 v[28:29], v[28:29], v[88:89], v[32:33]
	v_pk_fma_f32 v[50:51], v[30:31], v[58:59], v[50:51]
	v_pk_mul_f32 v[48:49], v[54:55], v[90:91]
	v_pk_fma_f32 v[50:51], v[26:27], v[78:79], v[50:51]
	v_lshlrev_b32_e32 v54, 16, v45
	v_and_b32_e32 v55, 0xffff0000, v45
	v_pk_fma_f32 v[44:45], v[22:23], v[54:55], v[50:51]
	v_pk_fma_f32 v[24:25], v[24:25], v[80:81], v[28:29]
	v_mul_f32_e32 v50, 0xbfb8aa3b, v44
	v_mul_f32_e32 v51, 0xbfb8aa3b, v45
	v_exp_f32_e32 v50, v50
	v_exp_f32_e32 v51, v51
	s_waitcnt vmcnt(0)
; __device__ __forceinline__ float siluf_(float x) { return x * sigmoidf_(x); }
; __device__ __forceinline__ void st_wt16(void* p, u32x4 v) { asm volatile("global_store_dwordx4 %0, %1, off sc1\n\ts_nop 1" : : "v"(p), "v"(v) : "memory"); }
; __device__ __forceinline__ void p_conv(const Params& p) {
;     ...
;         u32x4 raw[11];
; #pragma unroll
;         for (int i = 0; i < 11; ++i) {
;             const int rr = s0 - 3 + i;
;             if (seq0 + rr >= 0) raw[i] = __builtin_nontemporal_load((const u32x4*)(R1 + (size_t)(tok0 + rr) * 5120 + ch)); else raw[i] = (u32x4){0u, 0u, 0u, 0u};
;         }
; #pragma unroll
;         for (int i = 0; i < 8; ++i) {
;             float o[8];
; #pragma unroll
;             for (int e = 0; e < 8; ++e) o[e] = cb[e];
; #pragma unroll
;             for (int w = 0; w < 4; ++w) { float f[8]; unpack8(raw[i + w], f);
; #pragma unroll
;                 for (int e = 0; e < 8; ++e) o[e] += cw[w][e] * f[e]; }
; #pragma unroll
;             for (int e = 0; e < 8; ++e) o[e] = siluf_(o[e]) * scale;
;             st_wt16(QK + (size_t)(tok0 + s0 + i) * 2048 + ch, pack8(o));
;         }
	v_lshlrev_b32_e32 v28, 16, v40
	v_and_b32_e32 v29, 0xffff0000, v40
	v_pk_fma_f32 v[20:21], v[20:21], v[28:29], v[24:25]
	v_add_f32_e32 v50, 1.0, v50
	v_mul_f32_e32 v24, 0xbfb8aa3b, v20
	v_mul_f32_e32 v25, 0xbfb8aa3b, v21
	v_add_f32_e32 v51, 1.0, v51
	v_exp_f32_e32 v24, v24
	v_exp_f32_e32 v25, v25
	v_rcp_f32_e32 v50, v50
	v_rcp_f32_e32 v51, v51
	v_add_f32_e32 v24, 1.0, v24
	v_add_f32_e32 v25, 1.0, v25
	v_rcp_f32_e32 v24, v24
	v_pk_mul_f32 v[44:45], v[44:45], v[50:51]
	v_pk_fma_f32 v[50:51], v[14:15], v[64:65], v[18:19]
	v_rcp_f32_e32 v25, v25
	v_lshlrev_b32_e32 v68, 16, v46
	v_and_b32_e32 v69, 0xffff0000, v46
	v_pk_fma_f32 v[50:51], v[2:3], v[52:53], v[50:51]
	v_pk_fma_f32 v[0:1], v[0:1], v[86:87], v[12:13]
	v_pk_fma_f32 v[66:67], v[8:9], v[68:69], v[66:67]
	v_pk_fma_f32 v[50:51], v[6:7], v[82:83], v[50:51]
	v_lshlrev_b32_e32 v64, 16, v47
	v_and_b32_e32 v65, 0xffff0000, v47
	v_pk_fma_f32 v[0:1], v[4:5], v[68:69], v[0:1]
	v_lshlrev_b32_e32 v4, 16, v42
	v_and_b32_e32 v5, 0xffff0000, v42
	v_pk_fma_f32 v[12:13], v[14:15], v[52:53], v[18:19]
	v_pk_mul_f32 v[48:49], v[60:61], v[48:49] op_sel_hi:[0,1]
	v_mul_f32_e32 v61, 0xbfb8aa3b, v67
	v_pk_fma_f32 v[50:51], v[10:11], v[64:65], v[50:51]
	v_pk_fma_f32 v[0:1], v[8:9], v[4:5], v[0:1]
	v_pk_fma_f32 v[2:3], v[2:3], v[82:83], v[12:13]
	v_mul_f32_e32 v46, 0xbfb8aa3b, v66
	v_exp_f32_e32 v61, v61
	v_mul_f32_e32 v47, 0xbfb8aa3b, v50
	v_pk_mul_f32 v[20:21], v[20:21], v[24:25]
	v_pk_fma_f32 v[24:25], v[34:35], v[58:59], v[38:39]
	v_mul_f32_e32 v4, 0xbfb8aa3b, v0
	v_pk_fma_f32 v[2:3], v[6:7], v[64:65], v[2:3]
	v_lshlrev_b32_e32 v6, 16, v43
	v_and_b32_e32 v7, 0xffff0000, v43
	v_exp_f32_e32 v46, v46
	v_exp_f32_e32 v70, v47
	v_mul_f32_e32 v47, 0xbfb8aa3b, v51
	v_pk_fma_f32 v[24:25], v[30:31], v[78:79], v[24:25]
	v_exp_f32_e32 v8, v4
	v_mul_f32_e32 v4, 0xbfb8aa3b, v1
	v_pk_fma_f32 v[2:3], v[10:11], v[6:7], v[2:3]
	v_exp_f32_e32 v71, v47
	v_pk_fma_f32 v[24:25], v[26:27], v[54:55], v[24:25]
	v_lshlrev_b32_e32 v26, 16, v41
	v_and_b32_e32 v27, 0xffff0000, v41
	v_exp_f32_e32 v9, v4
	v_mul_f32_e32 v6, 0xbfb8aa3b, v2
	v_mul_f32_e32 v7, 0xbfb8aa3b, v3
	v_pk_fma_f32 v[22:23], v[22:23], v[26:27], v[24:25]
	v_exp_f32_e32 v6, v6
	v_exp_f32_e32 v7, v7
	v_add_f32_e32 v61, 1.0, v61
	v_mul_f32_e32 v24, 0xbfb8aa3b, v22
	v_mul_f32_e32 v25, 0xbfb8aa3b, v23
	v_add_f32_e32 v46, 1.0, v46
	v_rcp_f32_e32 v47, v61
	v_add_f32_e32 v61, 1.0, v70
	v_exp_f32_e32 v24, v24
	v_exp_f32_e32 v25, v25
	v_rcp_f32_e32 v46, v46
	v_rcp_f32_e32 v70, v61
	v_add_f32_e32 v61, 1.0, v71
	v_add_f32_e32 v8, 1.0, v8
	v_add_f32_e32 v9, 1.0, v9
	v_rcp_f32_e32 v71, v61
	v_rcp_f32_e32 v8, v8
	v_rcp_f32_e32 v9, v9
	v_add_f32_e32 v6, 1.0, v6
	v_add_f32_e32 v7, 1.0, v7
	v_rcp_f32_e32 v6, v6
	v_rcp_f32_e32 v7, v7
	v_add_f32_e32 v24, 1.0, v24
	v_add_f32_e32 v25, 1.0, v25
	v_pk_mul_f32 v[84:85], v[60:61], v[44:45] op_sel_hi:[0,1]
	v_pk_mul_f32 v[44:45], v[66:67], v[46:47]
	v_rcp_f32_e32 v24, v24
	v_rcp_f32_e32 v25, v25
	v_pk_mul_f32 v[46:47], v[60:61], v[44:45] op_sel_hi:[0,1]
	v_pk_mul_f32 v[44:45], v[50:51], v[70:71]
	v_pk_mul_f32 v[0:1], v[0:1], v[8:9]
	v_pk_mul_f32 v[50:51], v[60:61], v[44:45] op_sel_hi:[0,1]
	v_or_b32_e32 v44, 6, v74
	v_pk_mul_f32 v[8:9], v[60:61], v[0:1] op_sel_hi:[0,1]
	v_pk_mul_f32 v[0:1], v[2:3], v[6:7]
	v_ashrrev_i32_e32 v45, 31, v44
	v_pk_mul_f32 v[6:7], v[60:61], v[0:1] op_sel_hi:[0,1]
	v_or_b32_e32 v0, 7, v74
	v_lshlrev_b64 v[44:45], 12, v[44:45]
	v_pk_mul_f32 v[4:5], v[22:23], v[24:25]
	v_ashrrev_i32_e32 v1, 31, v0
	v_lshl_add_u64 v[66:67], v[76:77], 0, v[44:45]
	v_cvt_pk_bf16_f32 v44, v48, v49
	v_cvt_pk_bf16_f32 v45, v84, v85
	v_cvt_pk_bf16_f32 v46, v46, v47
	v_cvt_pk_bf16_f32 v47, v50, v51
	global_store_dwordx4 v[66:67], v[44:47], off sc1
	s_nop 1
	v_pk_mul_f32 v[20:21], v[60:61], v[20:21] op_sel_hi:[0,1]
	v_pk_mul_f32 v[4:5], v[60:61], v[4:5] op_sel_hi:[0,1]
	v_lshlrev_b64 v[0:1], 12, v[0:1]
	v_lshl_add_u64 v[10:11], v[76:77], 0, v[0:1]
	v_cvt_pk_bf16_f32 v0, v20, v21
	v_cvt_pk_bf16_f32 v1, v4, v5
	v_cvt_pk_bf16_f32 v2, v8, v9
	v_cvt_pk_bf16_f32 v3, v6, v7
	global_store_dwordx4 v[10:11], v[0:3], off sc1
	s_nop 1
	s_cbranch_scc0 .LBB0_183
